# out-projection epilogue: rolling window of 5 row-units of x loads behind counted vmcnt instead of a load/vmcnt(0)/fma/store ladder; plus A-unit Q loads issued together, inproj epilogue wait moved into
# baseline (speedup 1.0000x reference)
.LBB0_277:
	s_lshl_b32 s48, s35, 8
	s_add_i32 s48, s48, s39
	s_and_b64 s[8:9], s[0:1], s[8:9]
	v_or_b32_e32 v178, s48, v190
	v_cndmask_b32_e64 v68, 0, 1, s[8:9]
	v_ashrrev_i32_e32 v179, 31, v178
	v_cmp_ne_u32_e64 s[14:15], 1, v68
	s_andn2_b64 vcc, exec, s[8:9]
	v_or_b32_e32 v184, 16, v178
	v_or_b32_e32 v182, 32, v178
	v_or_b32_e32 v180, 48, v178
	s_cbranch_vccnz .LBB0_279
	v_lshlrev_b64 v[68:69], 6, v[178:179]
	v_lshl_add_u64 v[68:69], v[164:165], 0, v[68:69]
	v_ashrrev_i32_e32 v185, 31, v184
	global_load_dwordx4 v[152:155], v[68:69], off
	global_load_dwordx4 v[156:159], v[68:69], off offset:16
	v_lshlrev_b64 v[68:69], 6, v[184:185]
	v_lshl_add_u64 v[68:69], v[164:165], 0, v[68:69]
	v_ashrrev_i32_e32 v183, 31, v182
	global_load_dwordx4 v[112:115], v[68:69], off offset:16
	global_load_dwordx4 v[116:119], v[68:69], off
	v_lshlrev_b64 v[68:69], 6, v[182:183]
	v_lshl_add_u64 v[68:69], v[164:165], 0, v[68:69]
	v_ashrrev_i32_e32 v181, 31, v180
	global_load_dwordx4 v[88:91], v[68:69], off offset:16
	global_load_dwordx4 v[92:95], v[68:69], off
	v_lshlrev_b64 v[68:69], 6, v[180:181]
	v_lshl_add_u64 v[72:73], v[164:165], 0, v[68:69]
	global_load_dwordx4 v[68:71], v[72:73], off offset:16
	s_nop 0
	global_load_dwordx4 v[72:75], v[72:73], off
	s_waitcnt vmcnt(0)
.LBB0_279:
	s_and_b64 s[8:9], s[8:9], s[4:5]
	v_cndmask_b32_e64 v173, 0, v155, s[8:9]
	v_cndmask_b32_e64 v172, 1.0, v154, s[8:9]
	v_cndmask_b32_e64 v177, 0, v153, s[8:9]
	v_cndmask_b32_e64 v176, 1.0, v152, s[8:9]
	v_cndmask_b32_e64 v171, 0, v159, s[8:9]
	v_cndmask_b32_e64 v170, 1.0, v158, s[8:9]
	v_cndmask_b32_e64 v175, 0, v157, s[8:9]
	v_cndmask_b32_e64 v174, 1.0, v156, s[8:9]
	s_and_saveexec_b64 s[24:25], s[8:9]
	s_cbranch_execz .LBB0_281
	v_pk_mul_f32 v[154:155], v[148:149], v[176:177] op_sel:[1,1] op_sel_hi:[0,1]
	v_pk_mul_f32 v[152:153], v[148:149], v[176:177]
	v_pk_fma_f32 v[148:149], v[148:149], v[176:177], v[154:155] op_sel_hi:[1,0,1]
	v_pk_mul_f32 v[186:187], v[144:145], v[174:175] op_sel:[1,1] op_sel_hi:[0,1]
	v_mul_f32_e32 v148, v151, v173
	v_pk_fma_f32 v[156:157], v[150:151], v[172:173], v[148:149] op_sel_hi:[1,1,0] neg_lo:[0,0,1] neg_hi:[0,0,1]
	v_mul_f32_e32 v148, v150, v173
	v_pk_fma_f32 v[158:159], v[150:151], v[172:173], v[148:149] op_sel:[1,0,0] op_sel_hi:[0,1,0]
	v_pk_mul_f32 v[150:151], v[144:145], v[174:175]
	v_pk_fma_f32 v[144:145], v[144:145], v[174:175], v[186:187] op_sel_hi:[1,0,1]
	v_sub_f32_e32 v148, v152, v154
	v_mul_f32_e32 v144, v147, v171
	v_pk_fma_f32 v[188:189], v[146:147], v[170:171], v[144:145] op_sel_hi:[1,1,0] neg_lo:[0,0,1] neg_hi:[0,0,1]
	v_mul_f32_e32 v144, v146, v171
	v_pk_fma_f32 v[204:205], v[146:147], v[170:171], v[144:145] op_sel:[1,0,0] op_sel_hi:[0,1,0]
	v_sub_f32_e32 v144, v150, v186
	v_mov_b32_e32 v150, v156
	v_mov_b32_e32 v151, v158
	v_mov_b32_e32 v146, v188
	v_mov_b32_e32 v147, v204

.LBB0_476:
	s_lshl_b32 s0, s21, 1
	v_mov_b32_e32 v165, v197
	s_bfe_u32 s25, s0, 0x20002
	v_readfirstlane_b32 s24, v165
	s_lshl_b32 s3, s21, 4
	s_and_b32 s1, s0, 14
	s_ashr_i32 s23, s24, 7
	s_lshl_b32 s0, s25, 12
	s_and_b32 s3, s3, 0xf80
	s_or_b32 s3, s0, s3
	s_lshl_b32 s0, s23, 5
	v_and_b32_e32 v163, 31, v165
	s_add_i32 s3, s3, s0
	s_bfe_u32 s2, s21, 0x10008
	v_or_b32_e32 v0, s3, v163
	s_or_b32 s1, s1, s2
	v_ashrrev_i32_e32 v1, 31, v0
	s_ashr_i32 s26, s24, 6
	s_and_b32 s9, s1, 3
	v_lshlrev_b64 v[0:1], 10, v[0:1]
	s_and_b32 s2, s26, 1
	v_lshl_add_u64 v[0:1], s[76:77], 0, v[0:1]
	s_lshl_b32 s90, s9, 8
	v_bfe_u32 v164, v165, 5, 1
	v_lshl_add_u64 v[0:1], v[0:1], 0, s[90:91]
	s_lshl_b32 s90, s2, 7
	v_lshl_add_u64 v[0:1], v[0:1], 0, s[90:91]
	v_lshlrev_b32_e32 v194, 4, v164
	v_lshl_add_u64 v[0:1], v[0:1], 0, v[194:195]
	global_load_dwordx4 v[2:5], v[0:1], off
	global_load_dwordx4 v[80:83], v[0:1], off offset:32
	global_load_dwordx4 v[84:87], v[0:1], off offset:64
	global_load_dwordx4 v[88:91], v[0:1], off offset:96
	s_lshl_b32 s22, s9, 7
	s_lshl_b32 s8, s1, 20
	s_add_u32 s0, s10, s8
	s_addc_u32 s1, s11, 0
	s_lshl_b32 s25, s25, 6
	s_add_u32 s25, s14, s25
	s_addc_u32 s27, s15, 0
	s_lshl_b32 s9, s9, 4
	s_add_u32 s28, s25, s9
	s_addc_u32 s29, s27, 0
	s_lshl_b32 s9, s2, 3
	s_lshl_b32 s25, s26, 1
	v_and_or_b32 v11, s25, 2, v164
	v_lshlrev_b32_e32 v12, 6, v11
	s_and_b32 s27, s25, 4
	s_waitcnt vmcnt(3)
	v_lshlrev_b32_e32 v6, 16, v2
	v_and_b32_e32 v2, 0xffff0000, v2
	v_mul_f32_e32 v7, v2, v2
	v_mul_f32_e32 v2, 0x3e38aa3b, v2
	v_fmac_f32_e32 v7, v6, v6
	v_mul_f32_e32 v6, 0x3e38aa3b, v6
	v_cvt_pk_bf16_f32 v112, v6, v2
	v_lshlrev_b32_e32 v2, 16, v3
	v_and_b32_e32 v3, 0xffff0000, v3
	v_mul_f32_e32 v6, v3, v3
	v_mul_f32_e32 v3, 0x3e38aa3b, v3
	v_fmac_f32_e32 v6, v2, v2
	v_mul_f32_e32 v2, 0x3e38aa3b, v2
	v_cvt_pk_bf16_f32 v113, v2, v3
	v_and_b32_e32 v3, 0xffff0000, v4
	v_lshlrev_b32_e32 v2, 16, v4
	v_mul_f32_e32 v4, v3, v3
	v_mul_f32_e32 v3, 0x3e38aa3b, v3
	v_fmac_f32_e32 v4, v2, v2
	v_mul_f32_e32 v2, 0x3e38aa3b, v2
	v_cvt_pk_bf16_f32 v114, v2, v3
	v_and_b32_e32 v3, 0xffff0000, v5
	v_add_f32_e32 v6, v7, v6
	v_lshlrev_b32_e32 v2, 16, v5
	v_mul_f32_e32 v5, v3, v3
	v_add_f32_e32 v4, v4, v6
	v_fmac_f32_e32 v5, v2, v2
	v_mul_f32_e32 v2, 0x3e38aa3b, v2
	v_mul_f32_e32 v3, 0x3e38aa3b, v3
	v_add_f32_e32 v6, v5, v4
	v_cvt_pk_bf16_f32 v115, v2, v3
	s_waitcnt vmcnt(2)
	v_mov_b32_e32 v2, v80
	v_mov_b32_e32 v3, v81
	v_mov_b32_e32 v4, v82
	v_mov_b32_e32 v5, v83
	v_lshlrev_b32_e32 v7, 16, v2
	v_and_b32_e32 v2, 0xffff0000, v2
	v_mul_f32_e32 v8, v2, v2
	v_mul_f32_e32 v2, 0x3e38aa3b, v2
	v_fmac_f32_e32 v8, v7, v7
	v_mul_f32_e32 v7, 0x3e38aa3b, v7
	v_cvt_pk_bf16_f32 v116, v7, v2
	v_lshlrev_b32_e32 v2, 16, v3
	v_and_b32_e32 v3, 0xffff0000, v3
	v_mul_f32_e32 v7, v3, v3
	v_mul_f32_e32 v3, 0x3e38aa3b, v3
	v_fmac_f32_e32 v7, v2, v2
	v_mul_f32_e32 v2, 0x3e38aa3b, v2
	v_cvt_pk_bf16_f32 v117, v2, v3
	v_and_b32_e32 v3, 0xffff0000, v4
	v_lshlrev_b32_e32 v2, 16, v4
	v_mul_f32_e32 v4, v3, v3
	v_mul_f32_e32 v3, 0x3e38aa3b, v3
	v_add_f32_e32 v6, v6, v8
	v_fmac_f32_e32 v4, v2, v2
	v_mul_f32_e32 v2, 0x3e38aa3b, v2
	v_cvt_pk_bf16_f32 v118, v2, v3
	v_and_b32_e32 v3, 0xffff0000, v5
	v_add_f32_e32 v6, v7, v6
	v_lshlrev_b32_e32 v2, 16, v5
	v_mul_f32_e32 v5, v3, v3
	v_add_f32_e32 v4, v4, v6
	v_fmac_f32_e32 v5, v2, v2
	v_mul_f32_e32 v2, 0x3e38aa3b, v2
	v_mul_f32_e32 v3, 0x3e38aa3b, v3
	v_add_f32_e32 v10, v5, v4
	v_cvt_pk_bf16_f32 v119, v2, v3
	s_waitcnt vmcnt(1)
	v_mov_b32_e32 v2, v84
	v_mov_b32_e32 v3, v85
	v_mov_b32_e32 v4, v86
	v_mov_b32_e32 v5, v87
	v_lshlrev_b32_e32 v7, 16, v3
	v_lshlrev_b32_e32 v6, 16, v2
	v_and_b32_e32 v3, 0xffff0000, v3
	v_and_b32_e32 v2, 0xffff0000, v2
	v_pk_mul_f32 v[8:9], v[2:3], v[2:3]
	v_mul_f32_e32 v2, 0x3e38aa3b, v2
	v_pk_fma_f32 v[8:9], v[6:7], v[6:7], v[8:9]
	v_mul_f32_e32 v6, 0x3e38aa3b, v6
	v_cvt_pk_bf16_f32 v120, v6, v2
	v_mul_f32_e32 v2, 0x3e38aa3b, v7
	v_mul_f32_e32 v3, 0x3e38aa3b, v3
	v_cvt_pk_bf16_f32 v121, v2, v3
	v_lshlrev_b32_e32 v3, 16, v5
	v_lshlrev_b32_e32 v2, 16, v4
	v_and_b32_e32 v5, 0xffff0000, v5
	v_and_b32_e32 v4, 0xffff0000, v4
	v_pk_mul_f32 v[6:7], v[4:5], v[4:5]
	v_mul_f32_e32 v4, 0x3e38aa3b, v4
	v_pk_fma_f32 v[6:7], v[2:3], v[2:3], v[6:7]
	v_mul_f32_e32 v2, 0x3e38aa3b, v2
	v_cvt_pk_bf16_f32 v122, v2, v4
	v_mul_f32_e32 v2, 0x3e38aa3b, v3
	v_mul_f32_e32 v3, 0x3e38aa3b, v5
	v_cvt_pk_bf16_f32 v123, v2, v3
	v_add_f32_e32 v8, v10, v8
	v_add_f32_e32 v8, v9, v8
	v_add_f32_e32 v6, v6, v8
	v_add_f32_e32 v8, v7, v6
	v_lshlrev_b32_e32 v9, 4, v165
	s_waitcnt vmcnt(0)
	v_mov_b32_e32 v0, v88
	v_mov_b32_e32 v1, v89
	v_mov_b32_e32 v2, v90
	v_mov_b32_e32 v3, v91
	v_lshlrev_b32_e32 v5, 16, v1
	v_lshlrev_b32_e32 v4, 16, v0
	v_and_b32_e32 v1, 0xffff0000, v1
	v_and_b32_e32 v0, 0xffff0000, v0
	v_pk_mul_f32 v[6:7], v[0:1], v[0:1]
	v_mul_f32_e32 v0, 0x3e38aa3b, v0
	v_pk_fma_f32 v[6:7], v[4:5], v[4:5], v[6:7]
	v_mul_f32_e32 v4, 0x3e38aa3b, v4
	v_cvt_pk_bf16_f32 v124, v4, v0
	v_mul_f32_e32 v0, 0x3e38aa3b, v5
	v_mul_f32_e32 v1, 0x3e38aa3b, v1
	v_cvt_pk_bf16_f32 v125, v0, v1
	v_lshlrev_b32_e32 v1, 16, v3
	v_lshlrev_b32_e32 v0, 16, v2
	v_and_b32_e32 v3, 0xffff0000, v3
	v_and_b32_e32 v2, 0xffff0000, v2
	v_add_f32_e32 v6, v8, v6
	v_pk_mul_f32 v[4:5], v[2:3], v[2:3]
	v_add_f32_e32 v6, v7, v6
	v_pk_fma_f32 v[4:5], v[0:1], v[0:1], v[4:5]
	v_mul_f32_e32 v2, 0x3e38aa3b, v2
	v_mul_f32_e32 v1, 0x3e38aa3b, v1
	v_add_f32_e32 v4, v4, v6
	v_mul_f32_e32 v0, 0x3e38aa3b, v0
	v_cvt_pk_bf16_f32 v126, v0, v2
	v_mul_f32_e32 v2, 0x3e38aa3b, v3
	v_cvt_pk_bf16_f32 v127, v1, v2
	v_mov_b32_e32 v1, s9
	v_add_f32_e32 v0, v5, v4
	global_load_dwordx2 v[4:5], v1, s[28:29]
	v_bfe_u32 v1, v165, 2, 3
	v_lshrrev_b32_e32 v3, 1, v165
	s_lshl_b32 s9, s26, 2
	v_bfe_u32 v6, v165, 4, 2
	v_and_b32_e32 v8, 8, v3
	v_bitop3_b32 v11, s9, -13, v1 bitop3:0xc8
	v_or_b32_e32 v3, s9, v6
	v_bitop3_b32 v10, s9, v165, v6 bitop3:0x36
	v_or3_b32 v13, v11, s27, v8
	s_add_i32 s9, s26, 8
	v_and_b32_e32 v7, 48, v9
	v_lshlrev_b32_e32 v13, 8, v13
	s_lshl_b32 s25, s9, 2
	v_or3_b32 v14, v13, v12, v7
	v_bitop3_b32 v12, s25, v165, v6 bitop3:0x36
	s_lshl_b32 s28, s9, 1
	v_lshlrev_b32_e32 v12, 4, v12
	s_and_b32 s29, s28, 4
	v_or_b32_e32 v13, s25, v6
	v_and_b32_e32 v12, 0xf0, v12
	s_add_u32 s8, s12, s8
	v_lshl_or_b32 v15, v13, 8, v12
	v_and_or_b32 v13, s28, 2, v164
	s_addc_u32 s9, s13, 0
	s_lshl_b32 s30, s26, 10
	v_lshlrev_b32_e32 v10, 4, v10
	v_lshlrev_b32_e32 v16, 6, v13
	v_bitop3_b32 v13, s25, -13, v1 bitop3:0xc8
	s_add_i32 s25, s30, 0
	v_and_b32_e32 v10, 0xf0, v10
	v_or3_b32 v1, v13, s29, v8
	s_mov_b32 m0, s25
	v_lshl_or_b32 v3, v3, 8, v10
	v_lshlrev_b32_e32 v1, 8, v1
	global_load_lds_dwordx4 v14, s[0:1]
	s_add_i32 m0, s25, 0x4000
	v_or3_b32 v1, v1, v16, v7
	global_load_lds_dwordx4 v3, s[8:9]
	s_add_i32 m0, s25, 0x2000
	v_mov_b32_e32 v2, v0
	global_load_lds_dwordx4 v1, s[0:1]
	s_add_i32 m0, s25, 0x6000
	v_permlane32_swap_b32_e32 v0, v2
	global_load_lds_dwordx4 v15, s[8:9]
	s_add_u32 s8, s8, 0x4000
	s_addc_u32 s9, s9, 0
	s_add_u32 s0, s0, 0x4000
	s_addc_u32 s1, s1, 0
	s_add_i32 m0, s25, 0x8000
	s_nop 0
	global_load_lds_dwordx4 v14, s[0:1]
	s_add_i32 m0, s25, 0xc000
	s_nop 0
	global_load_lds_dwordx4 v3, s[8:9]
	s_add_i32 m0, s25, 0xa000
	s_nop 0
	global_load_lds_dwordx4 v1, s[0:1]
	s_add_i32 m0, s25, 0xe000
	s_cmp_lt_i32 s26, 4
	global_load_lds_dwordx4 v15, s[8:9]
	s_cbranch_scc1 .LBB0_478
	s_setprio 1

.LBB0_766:
	s_add_u32 s10, s8, 0xfffc0080
	s_addc_u32 s11, s9, -1
	s_add_i32 s38, 0, 0x10000
	v_add_u32_e32 v146, s38, v151
	ds_read_b128 v[120:123], v146
	ds_read_b128 v[124:127], v146 offset:1024
	ds_read_b128 v[142:145], v146 offset:2048
	ds_read_b128 v[146:149], v146 offset:3072
	s_cmp_eq_u32 s37, 12
	s_cselect_b32 s13, s1, s11
	s_cselect_b32 s12, s0, s10
	s_cselect_b32 s11, s7, s36
	s_cselect_b32 s10, s6, s35
	v_lshl_add_u64 v[186:187], s[8:9], 0, v[138:139]
	s_add_i32 m0, s20, 0xc000
	ds_read_b128 v[154:157], v153
	ds_read_b128 v[158:161], v153 offset:1024
	ds_read_b128 v[162:165], v153 offset:2048
	ds_read_b128 v[166:169], v153 offset:3072
	ds_read_b128 v[170:173], v153 offset:4096
	ds_read_b128 v[174:177], v153 offset:5120
	ds_read_b128 v[178:181], v153 offset:6144
	ds_read_b128 v[182:185], v153 offset:7168
	global_load_lds_dwordx4 v[186:187], off
	v_lshl_add_u64 v[186:187], s[8:9], 0, v[140:141]
	s_add_i32 m0, s20, 0xe000
	s_nop 0
	global_load_lds_dwordx4 v[186:187], off
	s_waitcnt lgkmcnt(8)
	s_barrier
	s_waitcnt lgkmcnt(0)
	s_setprio 1
	s_waitcnt lgkmcnt(0)
	v_mfma_f32_16x16x32_bf16 v[132:135], v[120:123], v[154:157], v[132:135]
	v_mfma_f32_16x16x32_bf16 v[128:131], v[142:145], v[154:157], v[128:131]
	v_mfma_f32_16x16x32_bf16 v[116:119], v[120:123], v[162:165], v[116:119]
	v_mfma_f32_16x16x32_bf16 v[112:115], v[142:145], v[162:165], v[112:115]
	v_mfma_f32_16x16x32_bf16 v[108:111], v[120:123], v[170:173], v[108:111]
	v_mfma_f32_16x16x32_bf16 v[104:107], v[142:145], v[170:173], v[104:107]
	v_mfma_f32_16x16x32_bf16 v[100:103], v[120:123], v[178:181], v[100:103]
	v_mfma_f32_16x16x32_bf16 v[96:99], v[142:145], v[178:181], v[96:99]
	v_mfma_f32_16x16x32_bf16 v[132:135], v[124:127], v[158:161], v[132:135]
	v_mfma_f32_16x16x32_bf16 v[128:131], v[146:149], v[158:161], v[128:131]
	v_mfma_f32_16x16x32_bf16 v[116:119], v[124:127], v[166:169], v[116:119]
	v_mfma_f32_16x16x32_bf16 v[112:115], v[146:149], v[166:169], v[112:115]
	v_mfma_f32_16x16x32_bf16 v[108:111], v[124:127], v[174:177], v[108:111]
	v_mfma_f32_16x16x32_bf16 v[104:107], v[146:149], v[174:177], v[104:107]
	v_mfma_f32_16x16x32_bf16 v[100:103], v[124:127], v[182:185], v[100:103]
	v_mfma_f32_16x16x32_bf16 v[96:99], v[146:149], v[182:185], v[96:99]
	s_setprio 0
	s_barrier
	s_add_i32 s40, 0, 0x14000
	s_add_i32 s38, s38, s19
	v_add_u32_e32 v208, s40, v151
	v_lshl_add_u64 v[212:213], s[10:11], 0, v[194:195]
	s_mov_b32 m0, s38
	ds_read_b128 v[186:189], v208
	ds_read_b128 v[190:193], v208 offset:1024
	ds_read_b128 v[204:207], v208 offset:2048
	ds_read_b128 v[208:211], v208 offset:3072
	global_load_lds_dwordx4 v[212:213], off
	v_lshl_add_u64 v[214:215], s[10:11], 0, v[136:137]
	s_add_i32 m0, s38, 0x2000
	s_nop 0
	global_load_lds_dwordx4 v[214:215], off
	s_barrier
	s_waitcnt lgkmcnt(0)
	s_setprio 1
	s_waitcnt lgkmcnt(0)
	v_mfma_f32_16x16x32_bf16 v[64:67], v[186:189], v[154:157], v[64:67]
	v_mfma_f32_16x16x32_bf16 v[56:59], v[204:207], v[154:157], v[56:59]
	v_mfma_f32_16x16x32_bf16 v[52:55], v[186:189], v[162:165], v[52:55]
	v_mfma_f32_16x16x32_bf16 v[48:51], v[204:207], v[162:165], v[48:51]
	v_mfma_f32_16x16x32_bf16 v[44:47], v[186:189], v[170:173], v[44:47]
	v_mfma_f32_16x16x32_bf16 v[40:43], v[204:207], v[170:173], v[40:43]
	v_mfma_f32_16x16x32_bf16 v[36:39], v[186:189], v[178:181], v[36:39]
	v_mfma_f32_16x16x32_bf16 v[32:35], v[204:207], v[178:181], v[32:35]
	v_mfma_f32_16x16x32_bf16 v[64:67], v[190:193], v[158:161], v[64:67]
	v_mfma_f32_16x16x32_bf16 v[56:59], v[208:211], v[158:161], v[56:59]
	v_mfma_f32_16x16x32_bf16 v[52:55], v[190:193], v[166:169], v[52:55]
	v_mfma_f32_16x16x32_bf16 v[48:51], v[208:211], v[166:169], v[48:51]
	v_mfma_f32_16x16x32_bf16 v[44:47], v[190:193], v[174:177], v[44:47]
	v_mfma_f32_16x16x32_bf16 v[40:43], v[208:211], v[174:177], v[40:43]
	v_mfma_f32_16x16x32_bf16 v[36:39], v[190:193], v[182:185], v[36:39]
	v_mfma_f32_16x16x32_bf16 v[32:35], v[208:211], v[182:185], v[32:35]
	s_setprio 0
	s_mov_b32 m0, s20
	v_lshl_add_u64 v[216:217], s[12:13], 0, v[194:195]
	s_barrier
	ds_read_b128 v[154:157], v153 offset:16384
	ds_read_b128 v[158:161], v153 offset:17408
	ds_read_b128 v[162:165], v153 offset:18432
	ds_read_b128 v[166:169], v153 offset:19456
	ds_read_b128 v[170:173], v153 offset:20480
	ds_read_b128 v[174:177], v153 offset:21504
	ds_read_b128 v[178:181], v153 offset:22528
	ds_read_b128 v[182:185], v153 offset:23552
	global_load_lds_dwordx4 v[216:217], off
	v_lshl_add_u64 v[236:237], s[12:13], 0, v[136:137]
	s_mov_b32 m0, s21
	s_nop 0
	global_load_lds_dwordx4 v[236:237], off
	s_barrier
	s_waitcnt lgkmcnt(0)
	s_setprio 1
	s_waitcnt lgkmcnt(0)
	v_mfma_f32_16x16x32_bf16 v[92:95], v[120:123], v[154:157], v[92:95]
	v_mfma_f32_16x16x32_bf16 v[88:91], v[142:145], v[154:157], v[88:91]
	v_mfma_f32_16x16x32_bf16 v[84:87], v[120:123], v[162:165], v[84:87]
	v_mfma_f32_16x16x32_bf16 v[80:83], v[142:145], v[162:165], v[80:83]
	v_mfma_f32_16x16x32_bf16 v[76:79], v[120:123], v[170:173], v[76:79]
	v_mfma_f32_16x16x32_bf16 v[72:75], v[142:145], v[170:173], v[72:75]
	v_mfma_f32_16x16x32_bf16 v[68:71], v[120:123], v[178:181], v[68:71]
	v_mfma_f32_16x16x32_bf16 v[60:63], v[142:145], v[178:181], v[60:63]
	v_mfma_f32_16x16x32_bf16 v[92:95], v[124:127], v[158:161], v[92:95]
	v_mfma_f32_16x16x32_bf16 v[88:91], v[146:149], v[158:161], v[88:91]
	v_mfma_f32_16x16x32_bf16 v[84:87], v[124:127], v[166:169], v[84:87]
	v_mfma_f32_16x16x32_bf16 v[80:83], v[146:149], v[166:169], v[80:83]
	v_mfma_f32_16x16x32_bf16 v[76:79], v[124:127], v[174:177], v[76:79]
	v_mfma_f32_16x16x32_bf16 v[72:75], v[146:149], v[174:177], v[72:75]
	v_mfma_f32_16x16x32_bf16 v[68:71], v[124:127], v[182:185], v[68:71]
	v_mfma_f32_16x16x32_bf16 v[60:63], v[146:149], v[182:185], v[60:63]
	s_setprio 0
	s_barrier
	s_add_u32 s38, s10, 0x40000
	s_addc_u32 s39, s11, 0
	s_add_i32 s40, s40, s19
	v_lshl_add_u64 v[120:121], s[38:39], 0, v[194:195]
	s_mov_b32 m0, s40
	s_nop 0
	global_load_lds_dwordx4 v[120:121], off
	v_lshl_add_u64 v[120:121], s[38:39], 0, v[136:137]
	s_add_i32 m0, s40, 0x2000
	s_nop 0
	global_load_lds_dwordx4 v[120:121], off
	s_waitcnt vmcnt(6)
	s_barrier
	s_setprio 1
	v_mfma_f32_16x16x32_bf16 v[28:31], v[186:189], v[154:157], v[28:31]
	v_mfma_f32_16x16x32_bf16 v[24:27], v[204:207], v[154:157], v[24:27]
	v_mfma_f32_16x16x32_bf16 v[20:23], v[186:189], v[162:165], v[20:23]
	v_mfma_f32_16x16x32_bf16 v[16:19], v[204:207], v[162:165], v[16:19]
	v_mfma_f32_16x16x32_bf16 v[12:15], v[186:189], v[170:173], v[12:15]
	v_mfma_f32_16x16x32_bf16 v[8:11], v[204:207], v[170:173], v[8:11]
	v_mfma_f32_16x16x32_bf16 v[4:7], v[186:189], v[178:181], v[4:7]
	v_mfma_f32_16x16x32_bf16 v[0:3], v[204:207], v[178:181], v[0:3]
	v_mfma_f32_16x16x32_bf16 v[28:31], v[190:193], v[158:161], v[28:31]
	v_mfma_f32_16x16x32_bf16 v[24:27], v[208:211], v[158:161], v[24:27]
	v_mfma_f32_16x16x32_bf16 v[20:23], v[190:193], v[166:169], v[20:23]
	v_mfma_f32_16x16x32_bf16 v[16:19], v[208:211], v[166:169], v[16:19]
	v_mfma_f32_16x16x32_bf16 v[12:15], v[190:193], v[174:177], v[12:15]
	v_mfma_f32_16x16x32_bf16 v[8:11], v[208:211], v[174:177], v[8:11]
	v_mfma_f32_16x16x32_bf16 v[4:7], v[190:193], v[182:185], v[4:7]
	v_mfma_f32_16x16x32_bf16 v[0:3], v[208:211], v[182:185], v[0:3]
	s_setprio 0
	s_add_i32 s38, 0, 0x18000
	v_add_u32_e32 v146, s38, v151
	s_barrier
	ds_read_b128 v[120:123], v146
	ds_read_b128 v[124:127], v146 offset:1024
	ds_read_b128 v[142:145], v146 offset:2048
	ds_read_b128 v[146:149], v146 offset:3072
	s_add_u32 s12, s12, 0x40000
	s_addc_u32 s13, s13, 0
	s_mov_b32 m0, s22
	v_lshl_add_u64 v[186:187], s[12:13], 0, v[194:195]
	ds_read_b128 v[154:157], v153 offset:32768
	ds_read_b128 v[158:161], v153 offset:33792
	ds_read_b128 v[162:165], v153 offset:34816
	ds_read_b128 v[166:169], v153 offset:35840
	ds_read_b128 v[170:173], v153 offset:36864
	ds_read_b128 v[174:177], v153 offset:37888
	ds_read_b128 v[178:181], v153 offset:38912
	ds_read_b128 v[182:185], v153 offset:39936
	global_load_lds_dwordx4 v[186:187], off
	v_lshl_add_u64 v[186:187], s[12:13], 0, v[136:137]
	s_mov_b32 m0, s23
	s_nop 0
	global_load_lds_dwordx4 v[186:187], off
	s_waitcnt lgkmcnt(8)
	s_barrier
	s_waitcnt lgkmcnt(0)
	s_setprio 1
	s_waitcnt lgkmcnt(0)
	v_mfma_f32_16x16x32_bf16 v[132:135], v[120:123], v[154:157], v[132:135]
	v_mfma_f32_16x16x32_bf16 v[128:131], v[142:145], v[154:157], v[128:131]
	v_mfma_f32_16x16x32_bf16 v[116:119], v[120:123], v[162:165], v[116:119]
	v_mfma_f32_16x16x32_bf16 v[112:115], v[142:145], v[162:165], v[112:115]
	v_mfma_f32_16x16x32_bf16 v[108:111], v[120:123], v[170:173], v[108:111]
	v_mfma_f32_16x16x32_bf16 v[104:107], v[142:145], v[170:173], v[104:107]
	v_mfma_f32_16x16x32_bf16 v[100:103], v[120:123], v[178:181], v[100:103]
	v_mfma_f32_16x16x32_bf16 v[96:99], v[142:145], v[178:181], v[96:99]
	v_mfma_f32_16x16x32_bf16 v[132:135], v[124:127], v[158:161], v[132:135]
	v_mfma_f32_16x16x32_bf16 v[128:131], v[146:149], v[158:161], v[128:131]
	v_mfma_f32_16x16x32_bf16 v[116:119], v[124:127], v[166:169], v[116:119]
	v_mfma_f32_16x16x32_bf16 v[112:115], v[146:149], v[166:169], v[112:115]
	v_mfma_f32_16x16x32_bf16 v[108:111], v[124:127], v[174:177], v[108:111]
	v_mfma_f32_16x16x32_bf16 v[104:107], v[146:149], v[174:177], v[104:107]
	v_mfma_f32_16x16x32_bf16 v[100:103], v[124:127], v[182:185], v[100:103]
	v_mfma_f32_16x16x32_bf16 v[96:99], v[146:149], v[182:185], v[96:99]
	s_setprio 0
	s_barrier
	s_add_i32 s12, 0, 0x1c000
	s_add_i32 s13, s38, s19
	v_add_u32_e32 v208, s12, v151
	v_lshl_add_u64 v[212:213], v[212:213], 0, s[82:83]
	s_mov_b32 m0, s13
	ds_read_b128 v[186:189], v208
	ds_read_b128 v[190:193], v208 offset:1024
	ds_read_b128 v[204:207], v208 offset:2048
	ds_read_b128 v[208:211], v208 offset:3072
	global_load_lds_dwordx4 v[212:213], off
	v_lshl_add_u64 v[212:213], v[214:215], 0, s[82:83]
	s_add_i32 m0, s13, 0x2000
	s_nop 0
	global_load_lds_dwordx4 v[212:213], off
	s_barrier
	s_waitcnt lgkmcnt(0)
	s_setprio 1
	s_waitcnt lgkmcnt(0)
	v_mfma_f32_16x16x32_bf16 v[64:67], v[186:189], v[154:157], v[64:67]
	v_mfma_f32_16x16x32_bf16 v[56:59], v[204:207], v[154:157], v[56:59]
	v_mfma_f32_16x16x32_bf16 v[52:55], v[186:189], v[162:165], v[52:55]
	v_mfma_f32_16x16x32_bf16 v[48:51], v[204:207], v[162:165], v[48:51]
	v_mfma_f32_16x16x32_bf16 v[44:47], v[186:189], v[170:173], v[44:47]
	v_mfma_f32_16x16x32_bf16 v[40:43], v[204:207], v[170:173], v[40:43]
	v_mfma_f32_16x16x32_bf16 v[36:39], v[186:189], v[178:181], v[36:39]
	v_mfma_f32_16x16x32_bf16 v[32:35], v[204:207], v[178:181], v[32:35]
	v_mfma_f32_16x16x32_bf16 v[64:67], v[190:193], v[158:161], v[64:67]
	v_mfma_f32_16x16x32_bf16 v[56:59], v[208:211], v[158:161], v[56:59]
	v_mfma_f32_16x16x32_bf16 v[52:55], v[190:193], v[166:169], v[52:55]
	v_mfma_f32_16x16x32_bf16 v[48:51], v[208:211], v[166:169], v[48:51]
	v_mfma_f32_16x16x32_bf16 v[44:47], v[190:193], v[174:177], v[44:47]
	v_mfma_f32_16x16x32_bf16 v[40:43], v[208:211], v[174:177], v[40:43]
	v_mfma_f32_16x16x32_bf16 v[36:39], v[190:193], v[182:185], v[36:39]
	v_mfma_f32_16x16x32_bf16 v[32:35], v[208:211], v[182:185], v[32:35]
	s_setprio 0
	s_mov_b32 m0, s26
	v_lshl_add_u64 v[212:213], v[216:217], 0, s[82:83]
	s_barrier
	ds_read_b128 v[154:157], v153 offset:49152
	ds_read_b128 v[158:161], v153 offset:50176
	ds_read_b128 v[162:165], v153 offset:51200
	ds_read_b128 v[166:169], v153 offset:52224
	ds_read_b128 v[170:173], v153 offset:53248
	ds_read_b128 v[174:177], v153 offset:54272
	ds_read_b128 v[178:181], v153 offset:55296
	ds_read_b128 v[182:185], v153 offset:56320
	global_load_lds_dwordx4 v[212:213], off
	v_lshl_add_u64 v[212:213], v[236:237], 0, s[82:83]
	s_mov_b32 m0, s27
	s_nop 0
	global_load_lds_dwordx4 v[212:213], off
	s_barrier
	s_waitcnt lgkmcnt(0)
	s_setprio 1
	s_waitcnt lgkmcnt(0)
	v_mfma_f32_16x16x32_bf16 v[92:95], v[120:123], v[154:157], v[92:95]
	v_mfma_f32_16x16x32_bf16 v[88:91], v[142:145], v[154:157], v[88:91]
	v_mfma_f32_16x16x32_bf16 v[84:87], v[120:123], v[162:165], v[84:87]
	v_mfma_f32_16x16x32_bf16 v[80:83], v[142:145], v[162:165], v[80:83]
	v_mfma_f32_16x16x32_bf16 v[76:79], v[120:123], v[170:173], v[76:79]
	v_mfma_f32_16x16x32_bf16 v[72:75], v[142:145], v[170:173], v[72:75]
	v_mfma_f32_16x16x32_bf16 v[68:71], v[120:123], v[178:181], v[68:71]
	v_mfma_f32_16x16x32_bf16 v[60:63], v[142:145], v[178:181], v[60:63]
	v_mfma_f32_16x16x32_bf16 v[92:95], v[124:127], v[158:161], v[92:95]
	v_mfma_f32_16x16x32_bf16 v[88:91], v[146:149], v[158:161], v[88:91]
	v_mfma_f32_16x16x32_bf16 v[84:87], v[124:127], v[166:169], v[84:87]
	v_mfma_f32_16x16x32_bf16 v[80:83], v[146:149], v[166:169], v[80:83]
	v_mfma_f32_16x16x32_bf16 v[76:79], v[124:127], v[174:177], v[76:79]
	v_mfma_f32_16x16x32_bf16 v[72:75], v[146:149], v[174:177], v[72:75]
	v_mfma_f32_16x16x32_bf16 v[68:71], v[124:127], v[182:185], v[68:71]
	v_mfma_f32_16x16x32_bf16 v[60:63], v[146:149], v[182:185], v[60:63]
	s_setprio 0
	s_barrier
	s_add_u32 s10, s10, 0x40080
	s_addc_u32 s11, s11, 0
	s_add_i32 s12, s12, s19
	v_lshl_add_u64 v[120:121], s[10:11], 0, v[194:195]
	s_mov_b32 m0, s12
	s_nop 0
	global_load_lds_dwordx4 v[120:121], off
	v_lshl_add_u64 v[120:121], s[10:11], 0, v[136:137]
	s_add_i32 m0, s12, 0x2000
	s_nop 0
	global_load_lds_dwordx4 v[120:121], off
	s_waitcnt vmcnt(6)
	s_barrier
	s_setprio 1
	v_mfma_f32_16x16x32_bf16 v[28:31], v[186:189], v[154:157], v[28:31]
	v_mfma_f32_16x16x32_bf16 v[24:27], v[204:207], v[154:157], v[24:27]
	v_mfma_f32_16x16x32_bf16 v[20:23], v[186:189], v[162:165], v[20:23]
	v_mfma_f32_16x16x32_bf16 v[16:19], v[204:207], v[162:165], v[16:19]
	v_mfma_f32_16x16x32_bf16 v[12:15], v[186:189], v[170:173], v[12:15]
	v_mfma_f32_16x16x32_bf16 v[8:11], v[204:207], v[170:173], v[8:11]
	v_mfma_f32_16x16x32_bf16 v[4:7], v[186:189], v[178:181], v[4:7]
	v_mfma_f32_16x16x32_bf16 v[0:3], v[204:207], v[178:181], v[0:3]
	v_mfma_f32_16x16x32_bf16 v[28:31], v[190:193], v[158:161], v[28:31]
	v_mfma_f32_16x16x32_bf16 v[24:27], v[208:211], v[158:161], v[24:27]
	v_mfma_f32_16x16x32_bf16 v[20:23], v[190:193], v[166:169], v[20:23]
	v_mfma_f32_16x16x32_bf16 v[16:19], v[208:211], v[166:169], v[16:19]
	v_mfma_f32_16x16x32_bf16 v[12:15], v[190:193], v[174:177], v[12:15]
	v_mfma_f32_16x16x32_bf16 v[8:11], v[208:211], v[174:177], v[8:11]
	v_mfma_f32_16x16x32_bf16 v[4:7], v[190:193], v[182:185], v[4:7]
	v_mfma_f32_16x16x32_bf16 v[0:3], v[208:211], v[182:185], v[0:3]
	s_setprio 0
	s_add_i32 s37, s37, 2
	s_add_u32 s8, s8, 0x100
	s_addc_u32 s9, s9, 0
	s_add_u32 s35, s35, 0x100
	s_addc_u32 s36, s36, 0
	s_cmp_gt_u32 s37, 13
	s_barrier
	s_cbranch_scc0 .LBB0_766
	s_lshr_b32 s8, s31, 4
	s_mulk_i32 s8, 0xc00
	s_ashr_i32 s9, s8, 31
	v_lshl_or_b32 v120, s34, 8, v152
	s_lshl_b64 s[8:9], s[8:9], 2
	s_add_u32 s8, s24, s8
	v_ashrrev_i32_e32 v121, 31, v120
	v_lshl_add_u32 v148, s31, 8, v150
	s_addc_u32 s9, s25, s9
	v_lshlrev_b64 v[146:147], 2, v[120:121]
	v_lshl_add_u64 v[142:143], s[8:9], 0, v[146:147]
	v_ashrrev_i32_e32 v149, 31, v148
	v_readlane_b32 s8, v252, 25
	v_lshlrev_b64 v[162:163], 12, v[148:149]
	v_readlane_b32 s9, v252, 26
	global_load_dwordx4 v[120:123], v[142:143], off offset:16
	global_load_dwordx4 v[124:127], v[142:143], off
	global_load_dwordx4 v[236:239], v[142:143], off offset:528
	global_load_dwordx4 v[240:243], v[142:143], off offset:512
	s_nop 3
	s_sub_u32 s42, s94, s8
	s_subb_u32 s43, s95, s9
	v_lshl_add_u64 v[144:145], s[8:9], 0, v[162:163]
	v_lshl_add_u64 v[144:145], v[144:145], 0, v[146:147]
	s_mov_b64 s[44:45], 0x10000
	v_lshl_add_u64 v[244:245], v[144:145], 0, s[44:45]
	s_mov_b64 s[44:45], 0x20000
	v_lshl_add_u64 v[246:247], v[144:145], 0, s[44:45]
	s_mov_b64 s[44:45], 0x30000
	v_lshl_add_u64 v[248:249], v[144:145], 0, s[44:45]
	s_mov_b64 s[44:45], 0x80000
	v_lshl_add_u64 v[250:251], v[144:145], 0, s[44:45]
	s_mov_b64 s[44:45], 0x90000
	v_lshl_add_u64 v[216:217], v[144:145], 0, s[44:45]
	s_mov_b64 s[44:45], 0xa0000
	v_lshl_add_u64 v[192:193], v[144:145], 0, s[44:45]
	s_mov_b64 s[44:45], 0xb0000
	v_lshl_add_u64 v[188:189], v[144:145], 0, s[44:45]
	s_and_b64 vcc, exec, s[4:5]
	s_mov_b32 s31, s30
	s_mov_b32 s34, s29
	s_mov_b64 s[10:11], s[6:7]
	global_load_dwordx4 v[154:157], v[144:145], off offset:16
	global_load_dwordx4 v[158:161], v[144:145], off offset:0
	global_load_dwordx4 v[164:167], v[244:245], off offset:16
	global_load_dwordx4 v[168:171], v[244:245], off offset:0
	global_load_dwordx4 v[172:175], v[246:247], off offset:16
	global_load_dwordx4 v[176:179], v[246:247], off offset:0
	global_load_dwordx4 v[180:183], v[248:249], off offset:16
	global_load_dwordx4 v[184:187], v[248:249], off offset:0
	global_load_dwordx4 v[204:207], v[250:251], off offset:16
	global_load_dwordx4 v[208:211], v[250:251], off offset:0
	s_waitcnt vmcnt(8)
	v_pk_fma_f32 v[128:129], v[128:129], v[120:121], v[154:155]
	v_pk_fma_f32 v[130:131], v[130:131], v[122:123], v[156:157]
	v_pk_fma_f32 v[132:133], v[132:133], v[124:125], v[158:159]
	v_pk_fma_f32 v[134:135], v[134:135], v[126:127], v[160:161]
	v_lshl_add_u64 v[190:191], v[144:145], 0, s[42:43]
	global_store_dwordx4 v[190:191], v[128:131], off offset:16
	global_store_dwordx4 v[190:191], v[132:135], off offset:0
	global_load_dwordx4 v[154:157], v[216:217], off offset:16
	global_load_dwordx4 v[158:161], v[216:217], off offset:0
	s_waitcnt vmcnt(10)
	v_pk_fma_f32 v[112:113], v[112:113], v[120:121], v[164:165]
	v_pk_fma_f32 v[114:115], v[114:115], v[122:123], v[166:167]
	v_pk_fma_f32 v[116:117], v[116:117], v[124:125], v[168:169]
	v_pk_fma_f32 v[118:119], v[118:119], v[126:127], v[170:171]
	v_lshl_add_u64 v[212:213], v[244:245], 0, s[42:43]
	global_store_dwordx4 v[212:213], v[112:115], off offset:16
	global_store_dwordx4 v[212:213], v[116:119], off offset:0
	global_load_dwordx4 v[164:167], v[192:193], off offset:16
	global_load_dwordx4 v[168:171], v[192:193], off offset:0
	s_waitcnt vmcnt(12)
	v_pk_fma_f32 v[104:105], v[104:105], v[120:121], v[172:173]
	v_pk_fma_f32 v[106:107], v[106:107], v[122:123], v[174:175]
	v_pk_fma_f32 v[108:109], v[108:109], v[124:125], v[176:177]
	v_pk_fma_f32 v[110:111], v[110:111], v[126:127], v[178:179]
	v_lshl_add_u64 v[190:191], v[246:247], 0, s[42:43]
	global_store_dwordx4 v[190:191], v[104:107], off offset:16
	global_store_dwordx4 v[190:191], v[108:111], off offset:0
	global_load_dwordx4 v[172:175], v[188:189], off offset:16
	global_load_dwordx4 v[176:179], v[188:189], off offset:0
	s_waitcnt vmcnt(14)
	v_pk_fma_f32 v[96:97], v[96:97], v[120:121], v[180:181]
	v_pk_fma_f32 v[98:99], v[98:99], v[122:123], v[182:183]
	v_pk_fma_f32 v[100:101], v[100:101], v[124:125], v[184:185]
	v_pk_fma_f32 v[102:103], v[102:103], v[126:127], v[186:187]
	v_lshl_add_u64 v[212:213], v[248:249], 0, s[42:43]
	global_store_dwordx4 v[212:213], v[96:99], off offset:16
	global_store_dwordx4 v[212:213], v[100:103], off offset:0
	global_load_dwordx4 v[180:183], v[144:145], off offset:528
	global_load_dwordx4 v[184:187], v[144:145], off offset:512
	s_waitcnt vmcnt(16)
	v_pk_fma_f32 v[88:89], v[88:89], v[120:121], v[204:205]
	v_pk_fma_f32 v[90:91], v[90:91], v[122:123], v[206:207]
	v_pk_fma_f32 v[92:93], v[92:93], v[124:125], v[208:209]
	v_pk_fma_f32 v[94:95], v[94:95], v[126:127], v[210:211]
	v_lshl_add_u64 v[190:191], v[250:251], 0, s[42:43]
	global_store_dwordx4 v[190:191], v[88:91], off offset:16
	global_store_dwordx4 v[190:191], v[92:95], off offset:0
	global_load_dwordx4 v[204:207], v[244:245], off offset:528
	global_load_dwordx4 v[208:211], v[244:245], off offset:512
	s_waitcnt vmcnt(16)
	v_pk_fma_f32 v[80:81], v[80:81], v[120:121], v[154:155]
	v_pk_fma_f32 v[82:83], v[82:83], v[122:123], v[156:157]
	v_pk_fma_f32 v[84:85], v[84:85], v[124:125], v[158:159]
	v_pk_fma_f32 v[86:87], v[86:87], v[126:127], v[160:161]
	v_lshl_add_u64 v[212:213], v[216:217], 0, s[42:43]
	global_store_dwordx4 v[212:213], v[80:83], off offset:16
	global_store_dwordx4 v[212:213], v[84:87], off offset:0
	global_load_dwordx4 v[154:157], v[246:247], off offset:528
	global_load_dwordx4 v[158:161], v[246:247], off offset:512
	s_waitcnt vmcnt(16)
	v_pk_fma_f32 v[72:73], v[72:73], v[120:121], v[164:165]
	v_pk_fma_f32 v[74:75], v[74:75], v[122:123], v[166:167]
	v_pk_fma_f32 v[76:77], v[76:77], v[124:125], v[168:169]
	v_pk_fma_f32 v[78:79], v[78:79], v[126:127], v[170:171]
	v_lshl_add_u64 v[190:191], v[192:193], 0, s[42:43]
	global_store_dwordx4 v[190:191], v[72:75], off offset:16
	global_store_dwordx4 v[190:191], v[76:79], off offset:0
	global_load_dwordx4 v[164:167], v[248:249], off offset:528
	global_load_dwordx4 v[168:171], v[248:249], off offset:512
	s_waitcnt vmcnt(16)
	v_pk_fma_f32 v[60:61], v[60:61], v[120:121], v[172:173]
	v_pk_fma_f32 v[62:63], v[62:63], v[122:123], v[174:175]
	v_pk_fma_f32 v[68:69], v[68:69], v[124:125], v[176:177]
	v_pk_fma_f32 v[70:71], v[70:71], v[126:127], v[178:179]
	v_lshl_add_u64 v[212:213], v[188:189], 0, s[42:43]
	global_store_dwordx4 v[212:213], v[60:63], off offset:16
	global_store_dwordx4 v[212:213], v[68:71], off offset:0
	global_load_dwordx4 v[172:175], v[250:251], off offset:528
	global_load_dwordx4 v[176:179], v[250:251], off offset:512
	s_waitcnt vmcnt(16)
	v_pk_fma_f32 v[56:57], v[56:57], v[236:237], v[180:181]
	v_pk_fma_f32 v[58:59], v[58:59], v[238:239], v[182:183]
	v_pk_fma_f32 v[64:65], v[64:65], v[240:241], v[184:185]
	v_pk_fma_f32 v[66:67], v[66:67], v[242:243], v[186:187]
	v_lshl_add_u64 v[190:191], v[144:145], 0, s[42:43]
	global_store_dwordx4 v[190:191], v[56:59], off offset:528
	global_store_dwordx4 v[190:191], v[64:67], off offset:512
	global_load_dwordx4 v[180:183], v[216:217], off offset:528
	global_load_dwordx4 v[184:187], v[216:217], off offset:512
	s_waitcnt vmcnt(16)
	v_pk_fma_f32 v[48:49], v[48:49], v[236:237], v[204:205]
	v_pk_fma_f32 v[50:51], v[50:51], v[238:239], v[206:207]
	v_pk_fma_f32 v[52:53], v[52:53], v[240:241], v[208:209]
	v_pk_fma_f32 v[54:55], v[54:55], v[242:243], v[210:211]
	v_lshl_add_u64 v[212:213], v[244:245], 0, s[42:43]
	global_store_dwordx4 v[212:213], v[48:51], off offset:528
	global_store_dwordx4 v[212:213], v[52:55], off offset:512
	global_load_dwordx4 v[204:207], v[192:193], off offset:528
	global_load_dwordx4 v[208:211], v[192:193], off offset:512
	s_waitcnt vmcnt(16)
	v_pk_fma_f32 v[40:41], v[40:41], v[236:237], v[154:155]
	v_pk_fma_f32 v[42:43], v[42:43], v[238:239], v[156:157]
	v_pk_fma_f32 v[44:45], v[44:45], v[240:241], v[158:159]
	v_pk_fma_f32 v[46:47], v[46:47], v[242:243], v[160:161]
	v_lshl_add_u64 v[190:191], v[246:247], 0, s[42:43]
	global_store_dwordx4 v[190:191], v[40:43], off offset:528
	global_store_dwordx4 v[190:191], v[44:47], off offset:512
	global_load_dwordx4 v[154:157], v[188:189], off offset:528
	global_load_dwordx4 v[158:161], v[188:189], off offset:512
	s_waitcnt vmcnt(16)
	v_pk_fma_f32 v[32:33], v[32:33], v[236:237], v[164:165]
	v_pk_fma_f32 v[34:35], v[34:35], v[238:239], v[166:167]
	v_pk_fma_f32 v[36:37], v[36:37], v[240:241], v[168:169]
	v_pk_fma_f32 v[38:39], v[38:39], v[242:243], v[170:171]
	v_lshl_add_u64 v[212:213], v[248:249], 0, s[42:43]
	global_store_dwordx4 v[212:213], v[32:35], off offset:528
	global_store_dwordx4 v[212:213], v[36:39], off offset:512
	s_waitcnt vmcnt(14)
	v_pk_fma_f32 v[24:25], v[24:25], v[236:237], v[172:173]
	v_pk_fma_f32 v[26:27], v[26:27], v[238:239], v[174:175]
	v_pk_fma_f32 v[28:29], v[28:29], v[240:241], v[176:177]
	v_pk_fma_f32 v[30:31], v[30:31], v[242:243], v[178:179]
	v_lshl_add_u64 v[190:191], v[250:251], 0, s[42:43]
	global_store_dwordx4 v[190:191], v[24:27], off offset:528
	global_store_dwordx4 v[190:191], v[28:31], off offset:512
	s_waitcnt vmcnt(12)
	v_pk_fma_f32 v[16:17], v[16:17], v[236:237], v[180:181]
	v_pk_fma_f32 v[18:19], v[18:19], v[238:239], v[182:183]
	v_pk_fma_f32 v[20:21], v[20:21], v[240:241], v[184:185]
	v_pk_fma_f32 v[22:23], v[22:23], v[242:243], v[186:187]
	v_lshl_add_u64 v[212:213], v[216:217], 0, s[42:43]
	global_store_dwordx4 v[212:213], v[16:19], off offset:528
	global_store_dwordx4 v[212:213], v[20:23], off offset:512
	s_waitcnt vmcnt(10)
	v_pk_fma_f32 v[8:9], v[8:9], v[236:237], v[204:205]
	v_pk_fma_f32 v[10:11], v[10:11], v[238:239], v[206:207]
	v_pk_fma_f32 v[12:13], v[12:13], v[240:241], v[208:209]
	v_pk_fma_f32 v[14:15], v[14:15], v[242:243], v[210:211]
	v_lshl_add_u64 v[190:191], v[192:193], 0, s[42:43]
	global_store_dwordx4 v[190:191], v[8:11], off offset:528
	global_store_dwordx4 v[190:191], v[12:15], off offset:512
	s_waitcnt vmcnt(8)
	v_pk_fma_f32 v[0:1], v[0:1], v[236:237], v[154:155]
	v_pk_fma_f32 v[2:3], v[2:3], v[238:239], v[156:157]
	v_pk_fma_f32 v[4:5], v[4:5], v[240:241], v[158:159]
	v_pk_fma_f32 v[6:7], v[6:7], v[242:243], v[160:161]
	v_lshl_add_u64 v[212:213], v[188:189], 0, s[42:43]
	global_store_dwordx4 v[212:213], v[0:3], off offset:528
	global_store_dwordx4 v[212:213], v[4:7], off offset:512
	s_mov_b64 s[8:9], s[0:1]
	s_cbranch_vccz .LBB0_763
	s_waitcnt vmcnt(0)
	s_cmpk_gt_u32 s14, 0xff
	s_cbranch_scc1 .LBB0_770
	s_barrier
